# in-proj: WGs 112..255 do their deferred weight copies before their 7 units (epilogues offset from the 8-unit WGs)
# speedup vs baseline: 1.0040x; 1.0005x over previous
.LBB0_206:
	s_cmp_lt_i32 s80, 3
	s_cselect_b64 s[2:3], -1, 0
	s_and_b64 s[0:1], s[2:3], s[0:1]
	s_andn2_b64 vcc, exec, s[0:1]
	s_cbranch_vccnz .LBB0_258
	s_add_u32 s4, s78, 0x200000
	s_addc_u32 s5, s79, 0
	v_readlane_b32 s7, v254, 4
	s_cmpk_lg_i32 s82, 0x100
	s_cbranch_scc1 .Lp2_body
	s_cmpk_lt_u32 s7, 0x70
	s_cbranch_scc1 .Lp2_body
	s_branch .Lp2_defer
.Lp2_body:
	s_add_u32 s4, s78, 0x200000
	s_addc_u32 s5, s79, 0
	v_readlane_b32 s7, v254, 4
	s_cmpk_gt_i32 s7, 0x76f
	v_readfirstlane_b32 s3, v193
	s_cbranch_scc1 .LBB0_223
	v_lshrrev_b32_e32 v0, 5, v193
	v_lshrrev_b32_e32 v2, 1, v193
	v_and_b32_e32 v0, 4, v0
	v_bfe_u32 v1, v193, 2, 2
	v_and_b32_e32 v11, 24, v2
	v_or3_b32 v0, v0, v1, v11
	v_lshlrev_b32_e32 v1, 4, v193
	v_add_u32_e32 v8, 0x2000, v1
	v_lshrrev_b32_e32 v2, 7, v8
	s_movk_i32 s2, 0xe0
	v_and_b32_e32 v4, 32, v193
	v_and_or_b32 v3, v2, s2, v0
	v_bitop3_b32 v9, v1, v4, 48 bitop3:0x6c
	v_and_b32_e32 v10, 64, v193
	v_bfe_u32 v12, v193, 2, 4
	s_movk_i32 s2, 0xf0
	v_or_b32_e32 v1, v9, v10
	v_and_or_b32 v2, v2, s2, v12
	s_add_u32 s33, s78, 0x6e00000
	v_lshl_or_b32 v130, v2, 11, v1
	v_lshrrev_b32_e32 v2, 3, v193
	s_movk_i32 s2, 0x60
	s_waitcnt lgkmcnt(0)
	s_addc_u32 s64, s79, 0
	v_and_or_b32 v0, v2, s2, v0
	s_movk_i32 s2, 0x70
	s_ashr_i32 s66, s7, 31
	v_lshl_or_b32 v132, v0, 11, v1
	v_and_or_b32 v0, v2, s2, v12
	s_lshr_b32 s2, s66, 29
	s_add_i32 s2, s7, s2
	s_lshr_b32 s10, s3, 6
	s_ashr_i32 s6, s2, 3
	s_and_b32 s2, s2, -8
	s_lshr_b32 s24, s3, 8
	s_lshl_b32 s65, s10, 10
	s_sub_i32 s2, s7, s2
	s_cmp_lt_i32 s2, 0
	s_movk_i32 s67, 0xef
	s_cselect_b32 s7, s67, 0xee
	s_mul_i32 s2, s2, s7
	s_add_i32 s2, s2, s6
	s_mul_hi_i32 s6, s2, 0x92492493
	s_add_i32 s6, s6, s2
	s_lshr_b32 s7, s6, 31
	s_ashr_i32 s6, s6, 5
	s_add_i32 s6, s6, s7
	s_lshl_b32 s7, s6, 3
	s_mul_i32 s6, s6, 56
	s_sub_i32 s6, s2, s6
	s_bfe_i32 s2, s6, 0x80000
	s_bfe_u32 s2, s2, 0x3000c
	s_add_i32 s8, s6, s2
	s_bfe_i32 s2, s8, 0x80000
	s_and_b32 s8, s8, 0xf8
	s_sub_i32 s6, s6, s8
	s_sext_i32_i16 s2, s2
	s_sext_i32_i8 s6, s6
	s_lshr_b32 s2, s2, 3
	s_add_i32 s52, s7, s6
	s_ashr_i32 s53, s52, 31
	s_bfe_i64 s[8:9], s[2:3], 0x100000
	s_lshl_b64 s[6:7], s[52:53], 19
	s_lshl_b64 s[8:9], s[8:9], 19
	s_add_u32 s58, s4, s8
	s_addc_u32 s59, s5, s9
	s_add_i32 s53, s65, 0
	s_add_i32 m0, s53, 0x10000
	v_lshl_or_b32 v128, v3, 11, v1
	global_load_lds_dwordx4 v132, s[58:59]
	s_add_i32 m0, s53, 0x12000
	s_add_u32 s8, s58, 0x40000
	global_load_lds_dwordx4 v128, s[58:59]
	s_addc_u32 s9, s59, 0
	s_add_i32 m0, s53, 0x14000
	v_lshl_or_b32 v134, v0, 11, v1
	global_load_lds_dwordx4 v132, s[8:9]
	s_add_i32 m0, s53, 0x16000
	s_add_u32 s54, s33, s6
	s_addc_u32 s55, s64, s7
	s_add_i32 s68, s53, 0x2000
	global_load_lds_dwordx4 v128, s[8:9]
	s_mov_b32 m0, s53
	s_add_u32 s6, s54, 0x40000
	global_load_lds_dwordx4 v134, s[54:55]
	s_mov_b32 m0, s68
	s_addc_u32 s7, s55, 0
	s_add_i32 s69, s53, 0x4000
	global_load_lds_dwordx4 v130, s[54:55]
	s_mov_b32 m0, s69
	s_add_i32 s70, s53, 0x6000
	global_load_lds_dwordx4 v134, s[6:7]
	s_mov_b32 m0, s70
	v_mov_b32_e32 v133, 0
	global_load_lds_dwordx4 v130, s[6:7]
	v_mov_b32_e32 v129, v133
	v_mov_b32_e32 v135, v133
	v_mov_b32_e32 v131, v133
	s_cmp_eq_u32 s24, 1
	s_mov_b32 s71, 0
	v_lshl_add_u64 v[6:7], s[58:59], 0, v[132:133]
	v_lshl_add_u64 v[4:5], s[58:59], 0, v[128:129]
	v_lshl_add_u64 v[0:1], s[54:55], 0, v[134:135]
	s_cselect_b64 s[6:7], -1, 0
	s_cmp_lg_u32 s24, 1
	v_lshl_add_u64 v[2:3], s[54:55], 0, v[130:131]
	s_cbranch_scc1 .LBB0_210
	s_barrier

.LBB0_223:
	s_branch .LBB0_258
.Lp2_defer_done:
	s_barrier
	s_branch .Lp2_body
.Lp2_defer:
	s_movk_i32 s2, 0x4200
	v_readlane_b32 s11, v254, 4
	v_mad_u32_u24 v2, v195, s2, 0
	s_lshl_b32 s2, s11, 3
	s_addk_i32 s2, 0xfc80
	v_add_u32_e32 v0, s2, v195
	s_movk_i32 s2, 0x180
	v_mul_lo_u32 v3, v0, s2
	v_and_b32_e32 v0, 31, v193
	v_bfe_u32 v32, v193, 5, 1
	v_lshl_add_u32 v5, v0, 2, v2
	s_movk_i32 s2, 0x84
	v_mad_u32_u24 v33, v32, s2, v5
	v_lshlrev_b32_e32 v4, 3, v193
	s_add_u32 s2, s78, 0x600000
	v_bfe_u32 v6, v193, 3, 3
	v_and_b32_e32 v4, 56, v4
	s_addc_u32 s3, s79, 0
	s_mul_i32 s10, s11, 48
	v_mul_u32_u24_e32 v8, 0x84, v4
	v_lshlrev_b32_e32 v9, 2, v6
	s_add_u32 s6, s78, 0x800000
	v_mad_u32_u24 v35, v195, 6, s10
	s_mul_i32 s10, s11, 0x60
	v_add3_u32 v34, v2, v8, v9
	v_lshlrev_b32_e32 v2, 10, v6
	s_addc_u32 s7, s79, 0
	v_mad_u32_u24 v36, v195, 12, s10
	s_mul_i32 s10, s11, 0x600
	v_mul_u32_u24_e32 v7, 0x84, v32
	v_or_b32_e32 v6, 0x2000, v2
	v_or_b32_e32 v8, 0x4000, v2
	v_or_b32_e32 v10, 0x6000, v2
	s_add_u32 s8, s78, 0x4800000
	v_add_u32_e32 v37, 0x12a000, v3
	s_movk_i32 s11, 0xc0
	v_mov_b32_e32 v3, s10
	v_mov_b32_e32 v1, 0
	s_movk_i32 s33, 0x2000
	s_addc_u32 s9, s79, 0
	v_mad_u32_u24 v38, v195, s11, v3
	s_waitcnt lgkmcnt(0)
	s_mov_b32 s36, -2
	s_movk_i32 s37, 0x37f
	s_movk_i32 s52, 0x57f
	s_movk_i32 s53, 0x1fff
	s_mov_b64 s[10:11], 0x40000
	s_mov_b32 s54, 0x92492493
	v_lshlrev_b32_e32 v0, 2, v0
	v_add_u32_e32 v39, v5, v7
	v_lshlrev_b32_e32 v2, 1, v2
	v_lshlrev_b32_e32 v4, 1, v4
	v_lshlrev_b32_e32 v6, 1, v6
	v_lshlrev_b32_e32 v8, 1, v8
	v_lshlrev_b32_e32 v10, 1, v10
	s_branch .LBB0_226
